# hot loop heads (GEMM K-loops, flash loops, compress loop) aligned to 64 bytes
# speedup vs baseline: 1.0052x; 1.0052x over previous
; template <class Epi>
; __device__ __forceinline__ void gemm_tile(const bf16_t* __restrict__ A, const bf16_t* __restrict__ Bt, int K, int row0, int col0, const Epi& epi, char* smem,
;                                           bool prefetched, bool nvalid, int nrow0, int ncol0) {
;     ...
;     for (int kt = 0; kt < nk; ++kt) {
;         const int cur = kt & 1;
;         if (kt + 1 < nk) GLDS_STAGE(cur ^ 1, pA, pB, kt + 1);
;         const char* cb = smem + cur * 2 * TILE_B;
; #pragma unroll
;         for (int ks = 0; ks < 2; ++ks) {
;             bf16x8 a[4], b[4];
; #pragma unroll
;             for (int m = 0; m < 4; ++m) a[m] = *(const bf16x8*)(cb + offA[m][ks]);
; #pragma unroll
;             for (int n = 0; n < 4; ++n) b[n] = *(const bf16x8*)(cb + offB[n][ks]);
.LBB0_154:
	v_readfirstlane_b32 s98, v64
	v_readfirstlane_b32 s99, v65
	v_readfirstlane_b32 s10, v66
	v_readfirstlane_b32 s100, v72
	v_readfirstlane_b32 s101, v73
	v_readfirstlane_b32 s13, v149
	s_nop 3
	s_sub_u32 s14, s10, s98
	s_and_b32 s98, s98, 0xffffff80
	s_and_b32 s100, s100, 0xffffff80
	s_nop 1
	v_subrev_u32_e32 v254, s98, v64
	v_subrev_u32_e32 v255, s100, v72
	s_add_i32 s12, s13, 0x8000
	s_mov_b32 m0, s12
	s_nop 0
	global_load_lds_dwordx4 v254, s[98:99]
	s_add_i32 m0, s12, 0x1000
	s_add_u32 s10, s98, s14
	s_addc_u32 s11, s99, 0
	global_load_lds_dwordx4 v254, s[10:11]
	s_add_i32 m0, s12, 0x2000
	s_add_u32 s10, s10, s14
	s_addc_u32 s11, s11, 0
	global_load_lds_dwordx4 v254, s[10:11]
	s_add_i32 m0, s12, 0x3000
	s_add_u32 s10, s10, s14
	s_addc_u32 s11, s11, 0
	global_load_lds_dwordx4 v254, s[10:11]
	s_add_u32 s98, s98, 0x80
	s_addc_u32 s99, s99, 0
	ds_read_b128 v[182:185], v139
	ds_read_b128 v[64:67], v142 offset:16384
	ds_read_b128 v[68:71], v142 offset:16896
	ds_read_b128 v[72:75], v142 offset:20480
	ds_read_b128 v[76:79], v142 offset:20992
	ds_read_b128 v[186:189], v139 offset:2048
	ds_read_b128 v[246:249], v139 offset:4096
	ds_read_b128 v[250:253], v139 offset:6144
	s_setprio 1
	.p2alignl 6, 3212836864

; template <class Epi>
; __device__ __forceinline__ void gemm_tile(const bf16_t* __restrict__ A, const bf16_t* __restrict__ Bt, int K, int row0, int col0, const Epi& epi, char* smem,
;                                           bool prefetched, bool nvalid, int nrow0, int ncol0) {
;     ...
;     for (int kt = 0; kt < nk; ++kt) {
;         const int cur = kt & 1;
;         if (kt + 1 < nk) GLDS_STAGE(cur ^ 1, pA, pB, kt + 1);
;         const char* cb = smem + cur * 2 * TILE_B;
; #pragma unroll
;         for (int ks = 0; ks < 2; ++ks) {
;             bf16x8 a[4], b[4];
; #pragma unroll
;             for (int m = 0; m < 4; ++m) a[m] = *(const bf16x8*)(cb + offA[m][ks]);
; #pragma unroll
;             for (int n = 0; n < 4; ++n) b[n] = *(const bf16x8*)(cb + offB[n][ks]);
.LBB0_197:
	v_readfirstlane_b32 s98, v106
	v_readfirstlane_b32 s99, v107
	v_readfirstlane_b32 s8, v108
	v_readfirstlane_b32 s100, v120
	v_readfirstlane_b32 s101, v121
	v_readfirstlane_b32 s11, v149
	s_nop 3
	s_sub_u32 s15, s8, s98
	s_and_b32 s98, s98, 0xffffff80
	s_and_b32 s100, s100, 0xffffff80
	s_nop 1
	v_subrev_u32_e32 v254, s98, v106
	v_subrev_u32_e32 v255, s100, v120
	s_add_i32 s10, s11, 0x8000
	s_mov_b32 m0, s10
	s_nop 0
	global_load_lds_dwordx4 v254, s[98:99]
	s_add_i32 m0, s10, 0x1000
	s_add_u32 s8, s98, s15
	s_addc_u32 s9, s99, 0
	global_load_lds_dwordx4 v254, s[8:9]
	s_add_i32 m0, s10, 0x2000
	s_add_u32 s8, s8, s15
	s_addc_u32 s9, s9, 0
	global_load_lds_dwordx4 v254, s[8:9]
	s_add_i32 m0, s10, 0x3000
	s_add_u32 s8, s8, s15
	s_addc_u32 s9, s9, 0
	global_load_lds_dwordx4 v254, s[8:9]
	s_add_u32 s98, s98, 0x80
	s_addc_u32 s99, s99, 0
	ds_read_b128 v[188:191], v117
	ds_read_b128 v[106:109], v130 offset:16384
	ds_read_b128 v[118:121], v130 offset:16896
	ds_read_b128 v[122:125], v130 offset:20480
	ds_read_b128 v[168:171], v130 offset:20992
	ds_read_b128 v[192:195], v117 offset:2048
	ds_read_b128 v[196:199], v117 offset:4096
	ds_read_b128 v[246:249], v117 offset:6144
	s_setprio 1
	.p2alignl 6, 3212836864

; __device__ __forceinline__ unsigned cvt_pk_bf16(float lo, float hi) { const f32x2_t f = {lo, hi}; return __builtin_bit_cast(unsigned, __builtin_convertvector(f, bf16x2_t)); }
; __device__ __forceinline__ float bf_lo(unsigned u) { return __uint_as_float(u << 16); }
; __device__ __forceinline__ float bf_hi(unsigned u) { return __uint_as_float(u & 0xffff0000u); }
; __device__ __forceinline__ f32x4 mfma16(bf16x8 a, bf16x8 b, f32x4 c) { return __builtin_amdgcn_mfma_f32_16x16x32_bf16(a, b, c, 0, 0, 0); }
; __device__ __forceinline__ void compress_task(const Params& p, int task, char* smem) {
;     ...
;     const int n = n0 + fr;
; #pragma unroll 2
;     for (int kq = 0; kq < 16; ++kq) {
;         const int kk = w * 16 + kq, l = kk >> 1, d = (kk & 1) * 32 + fq * 8;
;         int tok = 16 * n + l; tok = tok < S ? tok : S - 1;
;         const u32x4 raw = *(const u32x4*)(src + (size_t)tok * LDA + d);
;         const float* pp = pos + l * 64 + d;
;         const f32x4 p0 = *(const f32x4*)pp, p1 = *(const f32x4*)(pp + 4);
;         u32x4 ap;
;         ap.x = cvt_pk_bf16(bf_lo(raw.x) + p0[0], bf_hi(raw.x) + p0[1]);
;         ap.y = cvt_pk_bf16(bf_lo(raw.y) + p0[2], bf_hi(raw.y) + p0[3]);
;         ap.z = cvt_pk_bf16(bf_lo(raw.z) + p1[0], bf_hi(raw.z) + p1[1]);
;         ap.w = cvt_pk_bf16(bf_lo(raw.w) + p1[2], bf_hi(raw.w) + p1[3]);
;         const bf16x8 a = __builtin_bit_cast(bf16x8, ap);
; #pragma unroll
;         for (int nt = 0; nt < 16; ++nt) {
;             const bf16x8 bw = *(const bf16x8*)(w1t + (size_t)(nt * 16 + fr) * 2048 + kk * 32 + fq * 8);
;             acc[nt] = mfma16(bw, a, acc[nt]);
;         }
.LBB0_250:
	v_readfirstlane_b32 s98, v92
	v_readfirstlane_b32 s99, v93
	v_readfirstlane_b32 s100, v114
	s_mov_b32 s18, 0
	v_mbcnt_lo_u32_b32 v129, -1, 0
	v_mbcnt_hi_u32_b32 v129, -1, v129
	v_lshlrev_b32_e32 v129, 4, v129
	s_nop 3
	s_lshr_b32 s100, s100, 6
	s_lshl_b32 s101, s100, 10
	s_lshl_b32 s100, s100, 14
	s_sub_u32 s98, s98, s101
	s_subb_u32 s99, s99, 0
	s_add_u32 s98, s98, s100
	s_addc_u32 s99, s99, 0
	v_min_u32_e32 v117, 0xfff, v89
	v_mul_u32_u24_e32 v117, 0x880, v117
	v_lshlrev_b32_e32 v64, 1, v117
	s_nop 0
	v_lshl_add_u64 v[126:127], v[90:91], 0, v[64:65]
	global_load_dword v131, v[126:127], off
	v_add_u32_e32 v117, 1, v89
	v_min_u32_e32 v117, 0xfff, v117
	v_mul_u32_u24_e32 v117, 0x880, v117
	v_lshlrev_b32_e32 v64, 1, v117
	s_nop 0
	v_lshl_add_u64 v[126:127], v[90:91], 0, v[64:65]
	global_load_dword v131, v[126:127], off
	v_add_u32_e32 v117, 2, v89
	v_min_u32_e32 v117, 0xfff, v117
	v_mul_u32_u24_e32 v117, 0x880, v117
	v_lshlrev_b32_e32 v64, 1, v117
	s_nop 0
	v_lshl_add_u64 v[126:127], v[90:91], 0, v[64:65]
	global_load_dword v131, v[126:127], off
	v_add_u32_e32 v117, 3, v89
	v_min_u32_e32 v117, 0xfff, v117
	v_mul_u32_u24_e32 v117, 0x880, v117
	v_lshlrev_b32_e32 v64, 1, v117
	s_nop 0
	v_lshl_add_u64 v[126:127], v[90:91], 0, v[64:65]
	global_load_dword v131, v[126:127], off
	v_add_u32_e32 v117, 4, v89
	v_min_u32_e32 v117, 0xfff, v117
	v_mul_u32_u24_e32 v117, 0x880, v117
	v_lshlrev_b32_e32 v64, 1, v117
	s_nop 0
	v_lshl_add_u64 v[126:127], v[90:91], 0, v[64:65]
	global_load_dword v131, v[126:127], off
	v_add_u32_e32 v117, 5, v89
	v_min_u32_e32 v117, 0xfff, v117
	v_mul_u32_u24_e32 v117, 0x880, v117
	v_lshlrev_b32_e32 v64, 1, v117
	s_nop 0
	v_lshl_add_u64 v[126:127], v[90:91], 0, v[64:65]
	global_load_dword v131, v[126:127], off
	v_add_u32_e32 v117, 6, v89
	v_min_u32_e32 v117, 0xfff, v117
	v_mul_u32_u24_e32 v117, 0x880, v117
	v_lshlrev_b32_e32 v64, 1, v117
	s_nop 0
	v_lshl_add_u64 v[126:127], v[90:91], 0, v[64:65]
	global_load_dword v131, v[126:127], off
	v_add_u32_e32 v117, 7, v89
	v_min_u32_e32 v117, 0xfff, v117
	v_mul_u32_u24_e32 v117, 0x880, v117
	v_lshlrev_b32_e32 v64, 1, v117
	s_nop 0
	v_lshl_add_u64 v[126:127], v[90:91], 0, v[64:65]
	global_load_dword v131, v[126:127], off
	v_lshl_add_u64 v[110:111], v[96:97], 0, v[86:87]
	v_min_u32_e32 v117, 0xfff, v89
	v_mul_u32_u24_e32 v117, 0x880, v117
	global_load_dwordx4 v[166:169], v[110:111], off
	global_load_dwordx4 v[170:173], v[110:111], off offset:16
	v_lshlrev_b32_e32 v64, 1, v117
	s_nop 0
	v_lshl_add_u64 v[126:127], v[90:91], 0, v[64:65]
	global_load_dwordx4 v[162:165], v[126:127], off
	v_lshl_add_u64 v[110:111], v[94:95], 0, v[86:87]
	v_min_u32_e32 v117, 0xfff, v105
	v_mul_u32_u24_e32 v117, 0x880, v117
	global_load_dwordx4 v[246:249], v[110:111], off offset:128
	global_load_dwordx4 v[250:253], v[110:111], off offset:144
	v_lshlrev_b32_e32 v64, 1, v117
	s_nop 0
	v_lshl_add_u64 v[126:127], v[90:91], 0, v[64:65]
	global_load_dwordx4 v[174:177], v[126:127], off offset:64
	global_load_dwordx4 v[180:183], v129, s[98:99]
	s_add_u32 s100, s98, 0x10000
	s_addc_u32 s101, s99, 0
	global_load_dwordx4 v[184:187], v129, s[100:101]
	s_add_u32 s100, s98, 0x400
	s_addc_u32 s101, s99, 0
	global_load_dwordx4 v[188:191], v129, s[100:101]
	s_add_u32 s100, s98, 0x10400
	s_addc_u32 s101, s99, 0
	global_load_dwordx4 v[192:195], v129, s[100:101]
	s_add_u32 s100, s98, 0x20000
	s_addc_u32 s101, s99, 0
	global_load_dwordx4 v[196:199], v129, s[100:101]
	s_add_u32 s100, s98, 0x30000
	s_addc_u32 s101, s99, 0
	global_load_dwordx4 v[200:203], v129, s[100:101]
	s_add_u32 s100, s98, 0x20400
	s_addc_u32 s101, s99, 0
	global_load_dwordx4 v[204:207], v129, s[100:101]
	s_add_u32 s100, s98, 0x30400
	s_addc_u32 s101, s99, 0
	global_load_dwordx4 v[208:211], v129, s[100:101]
	s_add_u32 s100, s98, 0x40000
	s_addc_u32 s101, s99, 0
	global_load_dwordx4 v[212:215], v129, s[100:101]
	s_add_u32 s100, s98, 0x50000
	s_addc_u32 s101, s99, 0
	global_load_dwordx4 v[216:219], v129, s[100:101]
	s_add_u32 s100, s98, 0x40400
	s_addc_u32 s101, s99, 0
	global_load_dwordx4 v[220:223], v129, s[100:101]
	s_add_u32 s100, s98, 0x50400
	s_addc_u32 s101, s99, 0
	global_load_dwordx4 v[224:227], v129, s[100:101]
	s_add_u32 s100, s98, 0x60000
	s_addc_u32 s101, s99, 0
	global_load_dwordx4 v[228:231], v129, s[100:101]
	s_add_u32 s100, s98, 0x70000
	s_addc_u32 s101, s99, 0
	global_load_dwordx4 v[232:235], v129, s[100:101]
	s_add_u32 s100, s98, 0x60400
	s_addc_u32 s101, s99, 0
	global_load_dwordx4 v[236:239], v129, s[100:101]
	s_add_u32 s100, s98, 0x70400
	s_addc_u32 s101, s99, 0
	global_load_dwordx4 v[240:243], v129, s[100:101]
	.p2alignl 6, 3212836864

; template <int KW, int VD, bool SEL> ...
;     ...
;     if (!tiles) return;
;     int koff[NKI], voff[NVI];
; #pragma unroll
;     for (int i = 0; i < NKI; ++i) {
;         const int row = (w + 4 * i) * KRPI + lane / KCPR, cp = lane % KCPR;
;         const int f = (KW == 64) ? (((row >> 1) & 1) | (((row >> 3) & 1) << 1) | (((row >> 4) & 1) << 2)) : ((row & 3) | (((row >> 3) & 3) << 2));
;         koff[i] = row * ldk + (cp ^ f) * 8;
;     }
; #pragma unroll
;     for (int i = 0; i < NVI; ++i) {
;         const int row = (w + 4 * i) * 8 + (lane >> 3), cp = lane & 7;
;         voff[i] = row * S + (cp ^ ((row >> 1) & 7)) * 8;
;     }
;     ...
;     int j = __ffsll((long long)tiles) - 1; tiles &= tiles - 1;
;     FL_ISSUE(0, j);
;     asm volatile("s_waitcnt vmcnt(0)" ::: "memory");
;     __syncthreads();
;     int cur = 0;
;     const int kswz = (KW == 64) ? ((fr >> 1) & 7) : fr;
;     const int vswz = (fr >> 1) & 7;
; __device__ __forceinline__ void nsa_tile(const Params& p, int qb, int bg, char* smem) {
;     ...
;     u64 ormask = 0;
; #pragma unroll 4
;     for (int i = 0; i < 32; ++i) ormask |= selmask[i];
;     ormask = ((u64)__builtin_amdgcn_readfirstlane((unsigned)(ormask >> 32)) << 32) | (u64)__builtin_amdgcn_readfirstlane((unsigned)ormask);
;     const u64 selm[2] = {~0ull, ~0ull};
;     const int cur0 = t0 >> 6;
;     float* park = part;
;     __syncthreads();
; #pragma unroll
;     for (int qt = 0; qt < 2; ++qt)
; #pragma unroll
;         for (int dt = 0; dt < 4; ++dt)
;             ((f32x4*)park)[(qt * 4 + dt) * 256 + tid] = outacc[qt][dt];
.LBB0_366:
	s_add_i32 s1, s0, 0x11000
	s_add_i32 s2, s0, 0x11010
	v_mov_b32_e32 v3, s1
	v_mov_b32_e32 v58, s2
	ds_read_b128 v[54:57], v3
	ds_read_b128 v[58:61], v58
	s_add_i32 s0, s0, 32
	s_cmpk_eq_i32 s0, 0x100
	s_waitcnt lgkmcnt(1)
	v_or_b32_e32 v3, v54, v52
	v_or_b32_e32 v52, v55, v53
	v_or_b32_e32 v3, v56, v3
	v_or_b32_e32 v52, v57, v52
	s_waitcnt lgkmcnt(0)
	v_or_b32_e32 v3, v58, v3
	v_or_b32_e32 v53, v59, v52
	v_or_b32_e32 v52, v60, v3
	v_or_b32_e32 v53, v61, v53
	s_cbranch_scc0 .LBB0_366
	v_readlane_b32 s16, v244, 17
	v_readfirstlane_b32 s1, v53
	v_readfirstlane_b32 s0, v52
	v_readlane_b32 s17, v244, 18
	s_mov_b32 s2, s17
	s_mov_b32 s3, s1
	s_bfe_i64 s[0:1], s[0:1], 0x200000
	v_readlane_b32 s8, v244, 13
	s_or_b64 s[0:1], s[0:1], s[2:3]
	s_mul_i32 s2, s8, 0x1100000
	v_readlane_b32 s4, v245, 55
	v_readlane_b32 s5, v245, 56
	s_add_u32 s2, s4, s2
	s_addc_u32 s3, s5, 0
	v_readlane_b32 s5, v244, 12
	s_lshl_b32 s4, s5, 7
	s_add_u32 s6, s2, s4
	s_addc_u32 s7, s3, 0
	s_lshl_b32 s2, s8, 22
	s_lshl_b32 s3, s5, 19
	v_readlane_b32 s4, v245, 57
	s_add_u32 s2, s4, s2
	v_readlane_b32 s4, v245, 58
	s_addc_u32 s4, s4, 0
	s_add_u32 s8, s2, s3
	v_lshlrev_b32_e32 v122, 4, v76
	s_addc_u32 s9, s4, 0
	v_readlane_b32 s52, v244, 3
	v_pk_mul_f32 v[38:39], v[0:1], v[38:39] op_sel_hi:[0,1]
	v_pk_mul_f32 v[36:37], v[0:1], v[36:37] op_sel_hi:[0,1]
	v_pk_mul_f32 v[46:47], v[2:3], v[46:47] op_sel_hi:[0,1]
	v_pk_mul_f32 v[44:45], v[2:3], v[44:45] op_sel_hi:[0,1]
	v_pk_mul_f32 v[34:35], v[0:1], v[34:35] op_sel_hi:[0,1]
	v_pk_mul_f32 v[32:33], v[0:1], v[32:33] op_sel_hi:[0,1]
	v_pk_mul_f32 v[26:27], v[0:1], v[26:27] op_sel_hi:[0,1]
	v_pk_mul_f32 v[24:25], v[0:1], v[24:25] op_sel_hi:[0,1]
	v_pk_mul_f32 v[22:23], v[0:1], v[22:23] op_sel_hi:[0,1]
	v_pk_mul_f32 v[20:21], v[0:1], v[20:21] op_sel_hi:[0,1]
	v_add_u32_e32 v121, 0x9000, v122
	v_mov_b32_e32 v0, v114
	s_cmp_lg_u64 s[0:1], 0
	v_readlane_b32 s53, v244, 4
	v_readlane_b32 s54, v244, 5
	v_readlane_b32 s55, v244, 6
	v_readlane_b32 s56, v244, 7
	v_readlane_b32 s57, v244, 8
	v_readlane_b32 s58, v244, 9
	v_readlane_b32 s59, v244, 10
	s_mov_b64 s[18:19], 0x1000
	s_mov_b32 s20, 0xf149f2ca
	v_readlane_b32 s21, v244, 16
	v_pk_mul_f32 v[50:51], v[2:3], v[50:51] op_sel_hi:[0,1]
	v_pk_mul_f32 v[48:49], v[2:3], v[48:49] op_sel_hi:[0,1]
	v_pk_mul_f32 v[42:43], v[2:3], v[42:43] op_sel_hi:[0,1]
	v_pk_mul_f32 v[40:41], v[2:3], v[40:41] op_sel_hi:[0,1]
	v_pk_mul_f32 v[30:31], v[2:3], v[30:31] op_sel_hi:[0,1]
	v_pk_mul_f32 v[28:29], v[2:3], v[28:29] op_sel_hi:[0,1]
	s_barrier
	ds_write_b128 v122, v[44:47] offset:36864
	ds_write_b128 v122, v[48:51] offset:40960
	ds_write_b128 v122, v[40:43] offset:45056
	ds_write_b128 v122, v[28:31] offset:49152
	ds_write_b128 v122, v[32:35] offset:53248
	ds_write_b128 v122, v[36:39] offset:57344
	ds_write_b128 v122, v[24:27] offset:61440
	ds_write_b128 v121, v[20:23] offset:28672
	s_cbranch_scc0 .LBB0_387
	v_ashrrev_i32_e32 v2, 6, v0
	v_bfe_u32 v3, v0, 3, 3
	v_bfe_u32 v21, v0, 4, 1
	v_lshlrev_b32_e32 v22, 1, v2
	v_lshl_or_b32 v3, v2, 3, v3
	v_and_b32_e32 v20, 7, v0
	v_and_or_b32 v21, v22, 2, v21
	v_and_b32_e32 v22, 4, v22
	s_movk_i32 s2, 0x880
	v_bitop3_b32 v20, v21, v20, v22 bitop3:0x36
	v_mul_lo_u32 v21, v3, s2
	s_ff1_i32_b64 s4, s[0:1]
	s_add_u32 s2, s0, -1
	v_lshl_or_b32 v96, v20, 3, v21
	v_lshlrev_b32_e32 v20, 12, v3
	v_lshrrev_b32_e32 v3, 1, v3
	s_addc_u32 s3, s1, -1
	s_mul_i32 s5, s4, 0x44000
	v_xor_b32_e32 v3, v3, v0
	s_add_u32 s10, s6, s5
	v_lshlrev_b32_e32 v3, 3, v3
	v_lshlrev_b32_e32 v123, 10, v2
	s_addc_u32 s11, s7, 0
	v_ashrrev_i32_e32 v97, 31, v96
	v_add_u32_e32 v98, 0x11000, v96
	v_and_or_b32 v100, v3, 56, v20
	v_lshl_add_u64 v[2:3], v[96:97], 1, s[10:11]
	s_mov_b64 s[14:15], 0xc00
	v_readfirstlane_b32 s12, v123
	v_lshl_add_u64 v[2:3], v[2:3], 0, s[14:15]
	s_mov_b32 m0, s12
	v_ashrrev_i32_e32 v99, 31, v98
	v_add_u32_e32 v20, 0x1000, v123
	s_lshl_b32 s5, s4, 7
	global_load_lds_dwordx4 v[2:3], off
	v_lshl_add_u64 v[2:3], v[98:99], 1, s[10:11]
	v_readfirstlane_b32 s10, v20
	s_mov_b32 m0, s10
	s_add_u32 s10, s8, s5
	v_add_u32_e32 v20, 0x2000, v123
	v_add_u32_e32 v102, 0x20000, v100
	v_lshl_add_u64 v[2:3], v[2:3], 0, s[14:15]
	s_addc_u32 s11, s9, 0
	v_ashrrev_i32_e32 v101, 31, v100
	v_readfirstlane_b32 s5, v20
	v_add_u32_e32 v20, 0x3000, v123
	global_load_lds_dwordx4 v[2:3], off
	v_lshl_add_u64 v[2:3], v[100:101], 1, s[10:11]
	s_mov_b32 m0, s5
	v_ashrrev_i32_e32 v103, 31, v102
	v_readfirstlane_b32 s5, v20
	global_load_lds_dwordx4 v[2:3], off
	v_lshl_add_u64 v[2:3], v[102:103], 1, s[10:11]
	s_mov_b32 m0, s5
	v_lshrrev_b32_e32 v20, 1, v0
	global_load_lds_dwordx4 v[2:3], off
	v_bfe_u32 v2, v0, 4, 2
	v_and_b32_e32 v3, 15, v0
	v_bfe_u32 v21, v0, 1, 3
	v_lshlrev_b32_e32 v22, 1, v0
	v_and_b32_e32 v0, 3, v0
	v_bitop3_b32 v20, v2, v20, 7 bitop3:0x78
	s_waitcnt vmcnt(0)
	v_lshl_or_b32 v124, v3, 3, v108
	v_and_or_b32 v0, v22, 24, v0
	v_lshlrev_b32_e32 v125, 4, v20
	v_bitop3_b32 v20, v2, v21, 4 bitop3:0x36
	v_lshlrev_b32_e32 v127, 3, v2
	v_lshlrev_b32_e32 v128, 7, v3
	v_mov_b32_e32 v2, v1
	v_mov_b32_e32 v3, v1
	v_lshlrev_b32_e32 v126, 4, v20
	v_lshlrev_b32_e32 v129, 7, v0
	v_mov_b32_e32 v0, v1
	v_mov_b64_e32 v[22:23], v[2:3]
	v_mov_b64_e32 v[26:27], v[2:3]
	v_mov_b64_e32 v[30:31], v[2:3]
	v_mov_b64_e32 v[34:35], v[2:3]
	v_mov_b64_e32 v[38:39], v[2:3]
	v_mov_b64_e32 v[42:43], v[2:3]
	v_mov_b64_e32 v[46:47], v[2:3]
	v_mov_b64_e32 v[50:51], v[2:3]
	s_and_b64 s[2:3], s[2:3], s[0:1]
	s_mov_b32 s10, 0
	v_mov_b32_e32 v130, 0xf149f2ca
	v_mov_b32_e32 v104, 0
	v_mov_b64_e32 v[20:21], v[0:1]
	v_mov_b64_e32 v[24:25], v[0:1]
	v_mov_b64_e32 v[28:29], v[0:1]
	v_mov_b64_e32 v[32:33], v[0:1]
	v_mov_b64_e32 v[36:37], v[0:1]
	v_mov_b64_e32 v[40:41], v[0:1]
	v_mov_b64_e32 v[44:45], v[0:1]
	v_mov_b64_e32 v[48:49], v[0:1]
	v_mov_b32_e32 v105, 0
	v_mov_b32_e32 v0, 0xf149f2ca
	s_mov_b32 s16, 0xefa18f08
	v_lshlrev_b32_e32 v246, 1, v96
	v_lshlrev_b32_e32 v247, 1, v98
	v_lshlrev_b32_e32 v248, 1, v100
	v_lshlrev_b32_e32 v249, 1, v102
	s_waitcnt vmcnt(0) lgkmcnt(0)
	s_barrier
	s_cmp_lg_u64 s[2:3], 0
	s_cbranch_scc1 .LBB0_371
	s_branch .LBB0_370
	.p2alignl 6, 3212836864

; __device__ __forceinline__ f32x4 zero4() { return (f32x4){0.f, 0.f, 0.f, 0.f}; }
; #define NSA_GATE(qt, br) sigmoidf_(glog[qt][br])
; template <int KW, int VD, bool SEL> ...
;     ...
;     if (!tiles) return;
;     int koff[NKI], voff[NVI];
; #pragma unroll
;     for (int i = 0; i < NKI; ++i) {
;         const int row = (w + 4 * i) * KRPI + lane / KCPR, cp = lane % KCPR;
;         const int f = (KW == 64) ? (((row >> 1) & 1) | (((row >> 3) & 1) << 1) | (((row >> 4) & 1) << 2)) : ((row & 3) | (((row >> 3) & 3) << 2));
;         koff[i] = row * ldk + (cp ^ f) * 8;
;     }
; #pragma unroll
;     for (int i = 0; i < NVI; ++i) {
;         const int row = (w + 4 * i) * 8 + (lane >> 3), cp = lane & 7;
;         voff[i] = row * S + (cp ^ ((row >> 1) & 7)) * 8;
;     }
;     ...
;     int j = __ffsll((long long)tiles) - 1; tiles &= tiles - 1;
;     FL_ISSUE(0, j);
;     asm volatile("s_waitcnt vmcnt(0)" ::: "memory");
;     __syncthreads();
;     int cur = 0;
;     const int kswz = (KW == 64) ? ((fr >> 1) & 7) : fr;
;     const int vswz = (fr >> 1) & 7;
; __device__ __forceinline__ void nsa_tile(const Params& p, int qb, int bg, char* smem) {
;     ...
; #pragma unroll
;         for (int qt = 0; qt < 2; ++qt) {
;             const float sc = NSA_GATE(qt, 1) / lr[qt];
; #pragma unroll
;             for (int dt = 0; dt < 4; ++dt) ((f32x4*)park)[(qt * 4 + dt) * 256 + tid] = ((f32x4*)park)[(qt * 4 + dt) * 256 + tid] + O[qt][dt] * sc;
;         }
;     }
;     {
;         f32x4 O[2][4];
; #pragma unroll
;         for (int qt = 0; qt < 2; ++qt)
; #pragma unroll
;             for (int dt = 0; dt < 4; ++dt) O[qt][dt] = zero4();
;         float mr[2] = {-1e30f, -1e30f}, lr[2] = {0.f, 0.f};
;         const int lo[2] = {tpos[0] - 512, tpos[1] - 512};
;         const u64 ones[2] = {~0ull, ~0ull};
;         int jlo = t0 - 511; jlo = jlo < 0 ? 0 : (jlo >> 6);
;         const u64 upto = (cur0 == 63) ? ~0ull : ((1ull << (cur0 + 1)) - 1ull);
;         const u64 tiles = upto & ~((1ull << jlo) - 1ull);
;         flash_branch<64, 64, false>(tiles, projA + (size_t)b * S * LDA + 1792 + g * 64, LDA, projVT + ((size_t)b * 512 + 256 + g * 64) * S, 0,
;                                     qf, O, mr, lr, tpos, ones, lo, t0, t0 + 31 - 512, smem);
.LBB0_388:
	v_and_b32_e32 v0, 0xffff0000, v120
	v_mul_f32_e32 v0, 0xbfb8aa3b, v0
	v_exp_f32_e32 v0, v0
	v_lshlrev_b32_e32 v60, 16, v111
	ds_read_b128 v[52:55], v122 offset:36864
	ds_read_b128 v[56:59], v122 offset:40960
	v_readlane_b32 s3, v244, 15
	v_add_f32_e32 v0, 1.0, v0
	v_rcp_f32_e32 v0, v0
	s_lshr_b32 s2, s3, 1
	v_div_scale_f32 v61, s[0:1], v3, v3, v0
	v_rcp_f32_e32 v62, v61
	v_div_scale_f32 v63, vcc, v0, v3, v0
	v_fma_f32 v64, -v61, v62, 1.0
	v_fmac_f32_e32 v62, v64, v62
	v_mul_f32_e32 v64, v63, v62
	v_fma_f32 v65, -v61, v64, v63
	v_fmac_f32_e32 v64, v65, v62
	v_fma_f32 v61, -v61, v64, v63
	v_div_fmas_f32 v61, v61, v62, v64
	v_div_fixup_f32 v0, v61, v3, v0
	v_mul_f32_e32 v3, 0xbfb8aa3b, v60
	v_exp_f32_e32 v3, v3
	s_waitcnt lgkmcnt(1)
	v_pk_fma_f32 v[50:51], v[50:51], v[0:1], v[54:55] op_sel_hi:[1,0,1]
	v_pk_fma_f32 v[48:49], v[48:49], v[0:1], v[52:53] op_sel_hi:[1,0,1]
	ds_write_b128 v122, v[48:51] offset:36864
	ds_read_b128 v[48:51], v122 offset:45056
	v_add_f32_e32 v3, 1.0, v3
	v_rcp_f32_e32 v3, v3
	s_waitcnt lgkmcnt(2)
	v_pk_fma_f32 v[46:47], v[46:47], v[0:1], v[58:59] op_sel_hi:[1,0,1]
	v_pk_fma_f32 v[44:45], v[44:45], v[0:1], v[56:57] op_sel_hi:[1,0,1]
	ds_write_b128 v122, v[44:47] offset:40960
	ds_read_b128 v[44:47], v122 offset:49152
	s_waitcnt lgkmcnt(2)
	v_pk_fma_f32 v[42:43], v[42:43], v[0:1], v[50:51] op_sel_hi:[1,0,1]
	v_pk_fma_f32 v[40:41], v[40:41], v[0:1], v[48:49] op_sel_hi:[1,0,1]
	ds_write_b128 v122, v[40:43] offset:45056
	v_div_scale_f32 v40, s[0:1], v2, v2, v3
	v_rcp_f32_e32 v41, v40
	s_waitcnt lgkmcnt(1)
	v_pk_fma_f32 v[38:39], v[38:39], v[0:1], v[46:47] op_sel_hi:[1,0,1]
	v_pk_fma_f32 v[36:37], v[36:37], v[0:1], v[44:45] op_sel_hi:[1,0,1]
	ds_write_b128 v122, v[36:39] offset:49152
	v_fma_f32 v0, -v40, v41, 1.0
	v_fmac_f32_e32 v41, v0, v41
	v_div_scale_f32 v0, vcc, v3, v2, v3
	v_mul_f32_e32 v42, v0, v41
	v_fma_f32 v36, -v40, v42, v0
	v_fmac_f32_e32 v42, v36, v41
	ds_read_b128 v[36:39], v122 offset:53248
	v_fma_f32 v0, -v40, v42, v0
	s_add_i32 s0, s21, 0xfffffe01
	v_div_fmas_f32 v0, v0, v41, v42
	s_ashr_i32 s0, s0, 6
	v_div_fixup_f32 v0, v0, v2, v3
	s_cmp_gt_u32 s3, 15
	s_waitcnt lgkmcnt(0)
	v_pk_fma_f32 v[34:35], v[34:35], v[0:1], v[38:39] op_sel_hi:[1,0,1]
	v_pk_fma_f32 v[32:33], v[32:33], v[0:1], v[36:37] op_sel_hi:[1,0,1]
	s_cselect_b32 s3, s0, 0
	s_add_i32 s0, s2, 1
	ds_read_b128 v[40:43], v122 offset:57344
	ds_read_b128 v[36:39], v121 offset:28672
	ds_write_b128 v122, v[32:35] offset:53248
	ds_read_b128 v[32:35], v122 offset:61440
	s_lshl_b64 s[0:1], -1, s0
	s_not_b64 s[0:1], s[0:1]
	s_cmp_lg_u32 s2, 63
	s_cselect_b32 s1, s1, -1
	s_cselect_b32 s0, s0, -1
	s_lshl_b64 s[2:3], -1, s3
	s_and_b64 s[0:1], s[2:3], s[0:1]
	s_waitcnt lgkmcnt(3)
	v_pk_fma_f32 v[30:31], v[30:31], v[0:1], v[42:43] op_sel_hi:[1,0,1]
	v_pk_fma_f32 v[28:29], v[28:29], v[0:1], v[40:41] op_sel_hi:[1,0,1]
	s_waitcnt lgkmcnt(0)
	v_pk_fma_f32 v[26:27], v[26:27], v[0:1], v[34:35] op_sel_hi:[1,0,1]
	v_pk_fma_f32 v[24:25], v[24:25], v[0:1], v[32:33] op_sel_hi:[1,0,1]
	v_pk_fma_f32 v[22:23], v[22:23], v[0:1], v[38:39] op_sel_hi:[1,0,1]
	v_pk_fma_f32 v[20:21], v[20:21], v[0:1], v[36:37] op_sel_hi:[1,0,1]
	v_mov_b32_e32 v0, v114
	s_cmp_eq_u64 s[0:1], 0
	ds_write_b128 v122, v[28:31] offset:57344
	ds_write_b128 v122, v[24:27] offset:61440
	ds_write_b128 v121, v[20:23] offset:28672
	s_cbranch_scc1 .LBB0_337
	v_ashrrev_i32_e32 v2, 6, v0
	s_add_u32 s8, s8, 0x200000
	v_bfe_u32 v3, v0, 3, 3
	v_bfe_u32 v21, v0, 4, 1
	v_lshlrev_b32_e32 v22, 1, v2
	s_addc_u32 s9, s9, 0
	s_add_i32 s10, s21, 0xfffffe1f
	v_lshl_or_b32 v3, v2, 3, v3
	v_and_b32_e32 v20, 7, v0
	v_and_or_b32 v21, v22, 2, v21
	v_and_b32_e32 v22, 4, v22
	s_movk_i32 s2, 0x880
	v_bitop3_b32 v20, v21, v20, v22 bitop3:0x36
	v_mul_lo_u32 v21, v3, s2
	s_ff1_i32_b64 s4, s[0:1]
	s_add_u32 s2, s0, -1
	v_lshl_or_b32 v96, v20, 3, v21
	v_lshlrev_b32_e32 v20, 12, v3
	v_lshrrev_b32_e32 v3, 1, v3
	s_addc_u32 s3, s1, -1
	s_mul_i32 s5, s4, 0x44000
	v_xor_b32_e32 v3, v3, v0
	s_add_u32 s12, s6, s5
	v_lshlrev_b32_e32 v3, 3, v3
	v_lshlrev_b32_e32 v106, 10, v2
	s_addc_u32 s13, s7, 0
	v_ashrrev_i32_e32 v97, 31, v96
	v_add_u32_e32 v98, 0x11000, v96
	v_and_or_b32 v100, v3, 56, v20
	v_lshl_add_u64 v[2:3], v[96:97], 1, s[12:13]
	s_mov_b64 s[14:15], 0xe00
	v_readfirstlane_b32 s11, v106
	s_lshl_b32 s5, s4, 7
	v_lshl_add_u64 v[2:3], v[2:3], 0, s[14:15]
	s_mov_b32 m0, s11
	v_ashrrev_i32_e32 v99, 31, v98
	v_add_u32_e32 v20, 0x1000, v106
	global_load_lds_dwordx4 v[2:3], off
	v_lshl_add_u64 v[2:3], v[98:99], 1, s[12:13]
	v_readfirstlane_b32 s11, v20
	s_add_u32 s12, s8, s5
	v_add_u32_e32 v20, 0x2000, v106
	v_add_u32_e32 v102, 0x20000, v100
	v_lshl_add_u64 v[2:3], v[2:3], 0, s[14:15]
	s_mov_b32 m0, s11
	s_addc_u32 s13, s9, 0
	v_ashrrev_i32_e32 v101, 31, v100
	v_readfirstlane_b32 s5, v20
	v_add_u32_e32 v20, 0x3000, v106
	global_load_lds_dwordx4 v[2:3], off
	v_lshl_add_u64 v[2:3], v[100:101], 1, s[12:13]
	s_mov_b32 m0, s5
	v_ashrrev_i32_e32 v103, 31, v102
	v_readfirstlane_b32 s5, v20
	global_load_lds_dwordx4 v[2:3], off
	v_lshl_add_u64 v[2:3], v[102:103], 1, s[12:13]
	s_mov_b32 m0, s5
	v_lshrrev_b32_e32 v20, 1, v0
	global_load_lds_dwordx4 v[2:3], off
	v_bfe_u32 v2, v0, 4, 2
	v_and_b32_e32 v3, 15, v0
	v_bfe_u32 v21, v0, 1, 3
	v_lshlrev_b32_e32 v22, 1, v0
	v_and_b32_e32 v0, 3, v0
	v_bitop3_b32 v20, v2, v20, 7 bitop3:0x78
	s_waitcnt vmcnt(0)
	v_and_or_b32 v0, v22, 24, v0
	v_lshlrev_b32_e32 v123, 4, v20
	v_bitop3_b32 v20, v2, v21, 4 bitop3:0x36
	v_lshlrev_b32_e32 v125, 3, v2
	v_lshlrev_b32_e32 v126, 7, v3
	v_mov_b32_e32 v2, v1
	v_mov_b32_e32 v3, v1
	v_lshlrev_b32_e32 v124, 4, v20
	v_lshlrev_b32_e32 v127, 7, v0
	v_mov_b32_e32 v0, v1
	v_mov_b64_e32 v[22:23], v[2:3]
	v_mov_b64_e32 v[26:27], v[2:3]
	v_mov_b64_e32 v[30:31], v[2:3]
	v_mov_b64_e32 v[34:35], v[2:3]
	v_mov_b64_e32 v[38:39], v[2:3]
	v_mov_b64_e32 v[42:43], v[2:3]
	v_mov_b64_e32 v[46:47], v[2:3]
	v_mov_b64_e32 v[50:51], v[2:3]
	v_add_u32_e32 v107, 0xfffffe00, v94
	v_add_u32_e32 v120, 0xfffffe10, v94
	s_and_b64 s[2:3], s[2:3], s[0:1]
	s_mov_b32 s11, 0
	v_mov_b32_e32 v128, 0xf149f2ca
	v_mov_b32_e32 v104, 0
	v_mov_b64_e32 v[20:21], v[0:1]
	v_mov_b64_e32 v[24:25], v[0:1]
	v_mov_b64_e32 v[28:29], v[0:1]
	v_mov_b64_e32 v[32:33], v[0:1]
	v_mov_b64_e32 v[36:37], v[0:1]
	v_mov_b64_e32 v[40:41], v[0:1]
	v_mov_b64_e32 v[44:45], v[0:1]
	v_mov_b64_e32 v[48:49], v[0:1]
	v_mov_b32_e32 v105, 0
	v_mov_b32_e32 v0, 0xf149f2ca
	v_lshlrev_b32_e32 v250, 1, v96
	v_lshlrev_b32_e32 v251, 1, v98
	v_lshlrev_b32_e32 v252, 1, v100
	v_lshlrev_b32_e32 v253, 1, v102
	s_waitcnt vmcnt(0) lgkmcnt(0)
	s_barrier
	s_cmp_lg_u64 s[2:3], 0
	s_cbranch_scc1 .LBB0_392
	s_branch .LBB0_391
	.p2alignl 6, 3212836864

; template <class Epi>
; __device__ __forceinline__ void gemm_tile(const bf16_t* __restrict__ A, const bf16_t* __restrict__ Bt, int K, int row0, int col0, const Epi& epi, char* smem,
;                                           bool prefetched, bool nvalid, int nrow0, int ncol0) {
;     ...
;     for (int kt = 0; kt < nk; ++kt) {
;         const int cur = kt & 1;
;         if (kt + 1 < nk) GLDS_STAGE(cur ^ 1, pA, pB, kt + 1);
;         const char* cb = smem + cur * 2 * TILE_B;
; #pragma unroll
;         for (int ks = 0; ks < 2; ++ks) {
;             bf16x8 a[4], b[4];
; #pragma unroll
;             for (int m = 0; m < 4; ++m) a[m] = *(const bf16x8*)(cb + offA[m][ks]);
; #pragma unroll
;             for (int n = 0; n < 4; ++n) b[n] = *(const bf16x8*)(cb + offB[n][ks]);
.LBB0_460:
	v_readfirstlane_b32 s98, v94
	v_readfirstlane_b32 s99, v95
	v_readfirstlane_b32 s8, v96
	v_readfirstlane_b32 s100, v102
	v_readfirstlane_b32 s101, v103
	v_readfirstlane_b32 s12, v149
	s_nop 3
	s_sub_u32 s13, s8, s98
	s_and_b32 s98, s98, 0xffffff80
	s_and_b32 s100, s100, 0xffffff80
	s_nop 1
	v_subrev_u32_e32 v254, s98, v94
	v_subrev_u32_e32 v255, s100, v102
	s_add_i32 s11, s12, 0x8000
	s_mov_b32 m0, s11
	s_nop 0
	global_load_lds_dwordx4 v254, s[98:99]
	s_add_i32 m0, s11, 0x1000
	s_add_u32 s8, s98, s13
	s_addc_u32 s9, s99, 0
	global_load_lds_dwordx4 v254, s[8:9]
	s_add_i32 m0, s11, 0x2000
	s_add_u32 s8, s8, s13
	s_addc_u32 s9, s9, 0
	global_load_lds_dwordx4 v254, s[8:9]
	s_add_i32 m0, s11, 0x3000
	s_add_u32 s8, s8, s13
	s_addc_u32 s9, s9, 0
	global_load_lds_dwordx4 v254, s[8:9]
	s_add_u32 s98, s98, 0x80
	s_addc_u32 s99, s99, 0
	ds_read_b128 v[174:177], v110
	ds_read_b128 v[94:97], v87 offset:16384
	ds_read_b128 v[98:101], v87 offset:16896
	ds_read_b128 v[102:105], v87 offset:20480
	ds_read_b128 v[106:109], v87 offset:20992
	ds_read_b128 v[178:181], v110 offset:2048
	ds_read_b128 v[246:249], v110 offset:4096
	ds_read_b128 v[250:253], v110 offset:6144
	s_setprio 1
	.p2alignl 6, 3212836864

; template <class Epi>
; __device__ __forceinline__ void gemm_tile(const bf16_t* __restrict__ A, const bf16_t* __restrict__ Bt, int K, int row0, int col0, const Epi& epi, char* smem,
;                                           bool prefetched, bool nvalid, int nrow0, int ncol0) {
;     ...
;     for (int kt = 0; kt < nk; ++kt) {
;         const int cur = kt & 1;
;         if (kt + 1 < nk) GLDS_STAGE(cur ^ 1, pA, pB, kt + 1);
;         const char* cb = smem + cur * 2 * TILE_B;
; #pragma unroll
;         for (int ks = 0; ks < 2; ++ks) {
;             bf16x8 a[4], b[4];
; #pragma unroll
;             for (int m = 0; m < 4; ++m) a[m] = *(const bf16x8*)(cb + offA[m][ks]);
; #pragma unroll
;             for (int n = 0; n < 4; ++n) b[n] = *(const bf16x8*)(cb + offB[n][ks]);
.LBB0_563:
	v_readfirstlane_b32 s98, v110
	v_readfirstlane_b32 s99, v111
	v_readfirstlane_b32 s10, v118
	v_readfirstlane_b32 s100, v124
	v_readfirstlane_b32 s101, v125
	v_readfirstlane_b32 s17, v149
	s_nop 3
	s_sub_u32 s18, s10, s98
	s_and_b32 s98, s98, 0xffffff80
	s_and_b32 s100, s100, 0xffffff80
	s_nop 1
	v_subrev_u32_e32 v254, s98, v110
	v_subrev_u32_e32 v255, s100, v124
	s_add_i32 s13, s17, 0x8000
	s_mov_b32 m0, s13
	s_nop 0
	global_load_lds_dwordx4 v254, s[98:99]
	s_add_i32 m0, s13, 0x1000
	s_add_u32 s10, s98, s18
	s_addc_u32 s11, s99, 0
	global_load_lds_dwordx4 v254, s[10:11]
	s_add_i32 m0, s13, 0x2000
	s_add_u32 s10, s10, s18
	s_addc_u32 s11, s11, 0
	global_load_lds_dwordx4 v254, s[10:11]
	s_add_i32 m0, s13, 0x3000
	s_add_u32 s10, s10, s18
	s_addc_u32 s11, s11, 0
	global_load_lds_dwordx4 v254, s[10:11]
	s_add_u32 s98, s98, 0x80
	s_addc_u32 s99, s99, 0
	ds_read_b128 v[192:195], v85
	ds_read_b128 v[118:121], v142 offset:16384
	ds_read_b128 v[122:125], v142 offset:16896
	ds_read_b128 v[126:129], v142 offset:20480
	ds_read_b128 v[172:175], v142 offset:20992
	ds_read_b128 v[196:199], v85 offset:2048
	ds_read_b128 v[246:249], v85 offset:4096
	ds_read_b128 v[250:253], v85 offset:6144
	s_setprio 1
	.p2alignl 6, 3212836864

; template <class Epi>
; __device__ __forceinline__ void gemm_tile(const bf16_t* __restrict__ A, const bf16_t* __restrict__ Bt, int K, int row0, int col0, const Epi& epi, char* smem,
;                                           bool prefetched, bool nvalid, int nrow0, int ncol0) {
;     ...
;     for (int kt = 0; kt < nk; ++kt) {
;         const int cur = kt & 1;
;         if (kt + 1 < nk) GLDS_STAGE(cur ^ 1, pA, pB, kt + 1);
;         const char* cb = smem + cur * 2 * TILE_B;
; #pragma unroll
;         for (int ks = 0; ks < 2; ++ks) {
;             bf16x8 a[4], b[4];
; #pragma unroll
;             for (int m = 0; m < 4; ++m) a[m] = *(const bf16x8*)(cb + offA[m][ks]);
; #pragma unroll
;             for (int n = 0; n < 4; ++n) b[n] = *(const bf16x8*)(cb + offB[n][ks]);
.LBB0_619:
	v_readfirstlane_b32 s98, v92
	v_readfirstlane_b32 s99, v93
	v_readfirstlane_b32 s8, v94
	v_readfirstlane_b32 s100, v100
	v_readfirstlane_b32 s101, v101
	v_readfirstlane_b32 s12, v149
	s_nop 3
	s_sub_u32 s13, s8, s98
	s_and_b32 s98, s98, 0xffffff80
	s_and_b32 s100, s100, 0xffffff80
	s_nop 1
	v_subrev_u32_e32 v254, s98, v92
	v_subrev_u32_e32 v255, s100, v100
	s_add_i32 s11, s12, 0x8000
	s_mov_b32 m0, s11
	s_nop 0
	global_load_lds_dwordx4 v254, s[98:99]
	s_add_i32 m0, s11, 0x1000
	s_add_u32 s8, s98, s13
	s_addc_u32 s9, s99, 0
	global_load_lds_dwordx4 v254, s[8:9]
	s_add_i32 m0, s11, 0x2000
	s_add_u32 s8, s8, s13
	s_addc_u32 s9, s9, 0
	global_load_lds_dwordx4 v254, s[8:9]
	s_add_i32 m0, s11, 0x3000
	s_add_u32 s8, s8, s13
	s_addc_u32 s9, s9, 0
	global_load_lds_dwordx4 v254, s[8:9]
	s_add_u32 s98, s98, 0x80
	s_addc_u32 s99, s99, 0
	ds_read_b128 v[174:177], v108
	ds_read_b128 v[92:95], v110 offset:16384
	ds_read_b128 v[96:99], v110 offset:16896
	ds_read_b128 v[100:103], v110 offset:20480
	ds_read_b128 v[104:107], v110 offset:20992
	ds_read_b128 v[178:181], v108 offset:2048
	ds_read_b128 v[246:249], v108 offset:4096
	ds_read_b128 v[250:253], v108 offset:6144
	s_setprio 1
	.p2alignl 6, 3212836864

; template <class Epi>
; __device__ __forceinline__ void gemm_tile(const bf16_t* __restrict__ A, const bf16_t* __restrict__ Bt, int K, int row0, int col0, const Epi& epi, char* smem,
;                                           bool prefetched, bool nvalid, int nrow0, int ncol0) {
;     ...
;     for (int kt = 0; kt < nk; ++kt) {
;         const int cur = kt & 1;
;         if (kt + 1 < nk) GLDS_STAGE(cur ^ 1, pA, pB, kt + 1);
;         const char* cb = smem + cur * 2 * TILE_B;
; #pragma unroll
;         for (int ks = 0; ks < 2; ++ks) {
;             bf16x8 a[4], b[4];
; #pragma unroll
;             for (int m = 0; m < 4; ++m) a[m] = *(const bf16x8*)(cb + offA[m][ks]);
; #pragma unroll
;             for (int n = 0; n < 4; ++n) b[n] = *(const bf16x8*)(cb + offB[n][ks]);
.LBB0_723:
	v_readfirstlane_b32 s98, v64
	v_readfirstlane_b32 s99, v65
	v_readfirstlane_b32 s12, v66
	v_readfirstlane_b32 s100, v72
	v_readfirstlane_b32 s101, v73
	v_readfirstlane_b32 s15, v149
	s_nop 3
	s_sub_u32 s16, s12, s98
	s_and_b32 s98, s98, 0xffffff80
	s_and_b32 s100, s100, 0xffffff80
	s_nop 1
	v_subrev_u32_e32 v254, s98, v64
	v_subrev_u32_e32 v255, s100, v72
	s_add_i32 s14, s15, 0x8000
	s_mov_b32 m0, s14
	s_nop 0
	global_load_lds_dwordx4 v254, s[98:99]
	s_add_i32 m0, s14, 0x1000
	s_add_u32 s12, s98, s16
	s_addc_u32 s13, s99, 0
	global_load_lds_dwordx4 v254, s[12:13]
	s_add_i32 m0, s14, 0x2000
	s_add_u32 s12, s12, s16
	s_addc_u32 s13, s13, 0
	global_load_lds_dwordx4 v254, s[12:13]
	s_add_i32 m0, s14, 0x3000
	s_add_u32 s12, s12, s16
	s_addc_u32 s13, s13, 0
	global_load_lds_dwordx4 v254, s[12:13]
	s_add_u32 s98, s98, 0x80
	s_addc_u32 s99, s99, 0
	ds_read_b128 v[188:191], v137
	ds_read_b128 v[64:67], v143 offset:16384
	ds_read_b128 v[68:71], v143 offset:16896
	ds_read_b128 v[72:75], v143 offset:20480
	ds_read_b128 v[76:79], v143 offset:20992
	ds_read_b128 v[192:195], v137 offset:2048
	ds_read_b128 v[246:249], v137 offset:4096
	ds_read_b128 v[250:253], v137 offset:6144
	s_setprio 1
	.p2alignl 6, 3212836864

; template <class Epi>
; __device__ __forceinline__ void gemm_tile(const bf16_t* __restrict__ A, const bf16_t* __restrict__ Bt, int K, int row0, int col0, const Epi& epi, char* smem,
;                                           bool prefetched, bool nvalid, int nrow0, int ncol0) {
;     ...
;     for (int kt = 0; kt < nk; ++kt) {
;         const int cur = kt & 1;
;         if (kt + 1 < nk) GLDS_STAGE(cur ^ 1, pA, pB, kt + 1);
;         const char* cb = smem + cur * 2 * TILE_B;
; #pragma unroll
;         for (int ks = 0; ks < 2; ++ks) {
;             bf16x8 a[4], b[4];
; #pragma unroll
;             for (int m = 0; m < 4; ++m) a[m] = *(const bf16x8*)(cb + offA[m][ks]);
; #pragma unroll
;             for (int n = 0; n < 4; ++n) b[n] = *(const bf16x8*)(cb + offB[n][ks]);
.LBB0_766:
	v_readfirstlane_b32 s98, v106
	v_readfirstlane_b32 s99, v107
	v_readfirstlane_b32 s10, v108
	v_readfirstlane_b32 s100, v120
	v_readfirstlane_b32 s101, v121
	v_readfirstlane_b32 s13, v149
	s_nop 3
	s_sub_u32 s16, s10, s98
	s_and_b32 s98, s98, 0xffffff80
	s_and_b32 s100, s100, 0xffffff80
	s_nop 1
	v_subrev_u32_e32 v254, s98, v106
	v_subrev_u32_e32 v255, s100, v120
	s_add_i32 s12, s13, 0x8000
	s_mov_b32 m0, s12
	s_nop 0
	global_load_lds_dwordx4 v254, s[98:99]
	s_add_i32 m0, s12, 0x1000
	s_add_u32 s10, s98, s16
	s_addc_u32 s11, s99, 0
	global_load_lds_dwordx4 v254, s[10:11]
	s_add_i32 m0, s12, 0x2000
	s_add_u32 s10, s10, s16
	s_addc_u32 s11, s11, 0
	global_load_lds_dwordx4 v254, s[10:11]
	s_add_i32 m0, s12, 0x3000
	s_add_u32 s10, s10, s16
	s_addc_u32 s11, s11, 0
	global_load_lds_dwordx4 v254, s[10:11]
	s_add_u32 s98, s98, 0x80
	s_addc_u32 s99, s99, 0
	ds_read_b128 v[190:193], v128
	ds_read_b128 v[106:109], v131 offset:16384
	ds_read_b128 v[118:121], v131 offset:16896
	ds_read_b128 v[122:125], v131 offset:20480
	ds_read_b128 v[170:173], v131 offset:20992
	ds_read_b128 v[194:197], v128 offset:2048
	ds_read_b128 v[198:201], v128 offset:4096
	ds_read_b128 v[246:249], v128 offset:6144
	s_setprio 1
	.p2alignl 6, 3212836864

; __device__ __forceinline__ f32x4 zero4() { return (f32x4){0.f, 0.f, 0.f, 0.f}; }
; __device__ __forceinline__ void diff_tile(const Params& p, int qb, int bh, float lam, char* smem) {
;     int tid = threadIdx.x; asm volatile("" : "+v"(tid));
;     const int lane = tid & 63, w = tid >> 6, fr = lane & 15, fq = lane >> 4;
;     const int b = bh >> 3, h = bh & 7, map = w >> 1, half = w & 1, tw0 = qb * 64 + half * 32;
;     const bf16_t* projA = (const bf16_t*)(p.ws + OFF_PROJA);
;     const bf16_t* projVT = (const bf16_t*)(p.ws + OFF_PROJVT);
;     bf16x8 qf[2][2];
;     int tpos[2];
; #pragma unroll
;     for (int qt = 0; qt < 2; ++qt) {
;         tpos[qt] = tw0 + qt * 16 + fr;
;         const bf16_t* qrow = projA + (size_t)(b * S + tpos[qt]) * LDA + (h * 2 + map) * 64;
; #pragma unroll
;         for (int ks = 0; ks < 2; ++ks) qf[qt][ks] = *(const bf16x8*)(qrow + ks * 32 + fq * 8);
;     }
;     f32x4 O[2][8];
; #pragma unroll
;     for (int qt = 0; qt < 2; ++qt)
; #pragma unroll
;         for (int dt = 0; dt < 8; ++dt) O[qt][dt] = zero4();
;     float mr[2] = {-1e30f, -1e30f}, lr[2] = {0.f, 0.f};
;     const int lo[2] = {-1, -1};
;     const u64 ones[2] = {~0ull, ~0ull};
;     const u64 tiles = (qb == 63) ? ~0ull : ((1ull << (qb + 1)) - 1ull);
;     flash_branch<128, 128, false>(tiles, projA + (size_t)b * S * LDA + 1024 + h * 128, LDA, projVT + ((size_t)b * 1024 + h * 128) * S, map * 64,
;                                   qf, O, mr, lr, tpos, ones, lo, qb * 64, -1, smem);
; __global__ void __launch_bounds__(256, 2) fwd_megakernel(Params p) {
;     ...
;         for (int r = 0; r * G < 4096; ++r) {
;             const int k = (r & 1) ? (G - 1 - (int)blockIdx.x) : (int)blockIdx.x, i = r * G + k;
;             if (i < 4096) diff_tile(p, 63 - (i >> 6), i & 63, lam, smem);
.LBB0_817:
	s_setprio 3
	s_bitcmp0_b32 s17, 0
	v_readlane_b32 s7, v245, 0
	v_readlane_b32 s8, v245, 62
	s_cselect_b32 s7, s7, s8
	s_add_i32 s6, s7, s6
	s_cmpk_gt_i32 s6, 0xfff
	s_cbranch_scc1 .LBB0_816
	v_mov_b32_e32 v172, v114
	s_lshl_b32 s9, s6, 7
	s_and_b32 s18, s9, 0x380
	v_and_b32_e32 v0, 15, v172
	v_ashrrev_i32_e32 v173, 7, v172
	v_lshrrev_b32_e32 v1, 1, v172
	s_and_b32 s7, s6, 0xffffffc0
	v_and_or_b32 v171, v1, 32, v0
	v_lshl_add_u32 v0, v173, 6, s18
	v_readlane_b32 s20, v245, 55
	v_bfe_u32 v170, v172, 4, 2
	s_sub_i32 s19, 0xfc0, s7
	v_ashrrev_i32_e32 v1, 31, v0
	v_readlane_b32 s21, v245, 56
	s_bfe_u32 s8, s6, 0x30003
	v_or_b32_e32 v127, s19, v171
	v_lshl_add_u64 v[0:1], v[0:1], 1, s[20:21]
	v_lshlrev_b32_e32 v124, 4, v170
	v_mov_b32_e32 v125, v119
	s_lshl_b32 s7, s8, 12
	v_lshl_add_u64 v[0:1], v[0:1], 0, v[124:125]
	v_or_b32_e32 v125, 16, v127
	v_add_u32_e32 v118, s7, v127
	v_add_u32_e32 v126, s7, v125
	v_mad_u64_u32 v[2:3], s[10:11], v118, s3, v[0:1]
	v_mad_u64_u32 v[0:1], s[10:11], v126, s3, v[0:1]
	global_load_dwordx4 v[64:67], v[2:3], off
	global_load_dwordx4 v[68:71], v[2:3], off offset:64
	global_load_dwordx4 v[72:75], v[0:1], off
	global_load_dwordx4 v[76:79], v[0:1], off offset:64
	s_ashr_i32 s7, s6, 6
	s_sub_i32 s7, 64, s7
	s_lshl_b64 s[10:11], -1, s7
	s_not_b64 s[10:11], s[10:11]
	s_cmp_gt_u32 s6, 63
	s_cselect_b32 s7, s11, -1
	s_cselect_b32 s6, s10, -1
	v_mov_b32_e32 v0, v114
	s_cmp_eq_u64 s[6:7], 0
	s_cbranch_scc1 .LBB0_838
; template <int KW, int VD, bool SEL> ...
;     constexpr int KROWB = KW * 2, KB = 64 * KROWB, VB = VD * 128, BUFB = KB + VB;
;     constexpr int NKI = KB / 4096, NVI = VB / 4096, KRPI = 1024 / KROWB, KCPR = KROWB / 16;
;     int tid = threadIdx.x; asm volatile("" : "+v"(tid));
;     const int lane = tid & 63, w = tid >> 6, fr = lane & 15, fq = lane >> 4;
;     if (!tiles) return;
;     int koff[NKI], voff[NVI];
; #pragma unroll
;     for (int i = 0; i < NKI; ++i) {
;         const int row = (w + 4 * i) * KRPI + lane / KCPR, cp = lane % KCPR;
;         const int f = (KW == 64) ? (((row >> 1) & 1) | (((row >> 3) & 1) << 1) | (((row >> 4) & 1) << 2)) : ((row & 3) | (((row >> 3) & 3) << 2));
;         koff[i] = row * ldk + (cp ^ f) * 8;
;     }
; #pragma unroll
;     for (int i = 0; i < NVI; ++i) {
;         const int row = (w + 4 * i) * 8 + (lane >> 3), cp = lane & 7;
;         voff[i] = row * S + (cp ^ ((row >> 1) & 7)) * 8;
;     }
;     ...
;     int j = __ffsll((long long)tiles) - 1; tiles &= tiles - 1;
;     FL_ISSUE(0, j);
;     asm volatile("s_waitcnt vmcnt(0)" ::: "memory");
;     __syncthreads();
;     int cur = 0;
;     const int kswz = (KW == 64) ? ((fr >> 1) & 7) : fr;
;     const int vswz = (fr >> 1) & 7;
;     while (true) {
	v_ashrrev_i32_e32 v2, 6, v0
	v_bfe_u32 v1, v0, 4, 2
	v_lshlrev_b32_e32 v3, 2, v2
	v_lshlrev_b32_e32 v6, 1, v2
	v_and_b32_e32 v4, 15, v0
	v_or_b32_e32 v5, v3, v1
	v_and_b32_e32 v6, 12, v6
	s_mul_i32 s9, s8, 0x1100000
	v_mul_lo_u32 v5, v5, s12
	v_bitop3_b32 v6, v6, v4, v1 bitop3:0x36
	s_add_u32 s9, s20, s9
	v_lshl_or_b32 v128, v6, 3, v5
	v_add_u32_e32 v5, 16, v3
	s_addc_u32 s10, s21, 0
	s_lshl_b32 s11, s18, 1
	v_or_b32_e32 v6, v5, v1
	v_lshrrev_b32_e32 v5, 1, v5
	s_add_u32 s20, s9, s11
	v_and_b32_e32 v5, 12, v5
	s_addc_u32 s21, s10, 0
	s_lshl_b32 s8, s8, 23
	v_readlane_b32 s9, v245, 57
	v_mul_lo_u32 v6, v6, s12
	v_bitop3_b32 v5, v5, v4, v1 bitop3:0x36
	v_add_u32_e32 v3, 48, v3
	s_add_u32 s8, s9, s8
	v_readlane_b32 s9, v245, 58
	v_lshl_or_b32 v130, v5, 3, v6
	v_or_b32_e32 v5, v3, v1
	v_lshrrev_b32_e32 v3, 1, v3
	s_addc_u32 s9, s9, 0
	s_lshl_b32 s10, s18, 13
	v_and_b32_e32 v3, 12, v3
	s_add_u32 s22, s8, s10
	v_mul_lo_u32 v5, v5, s12
	v_bitop3_b32 v3, v3, v4, v1 bitop3:0x36
	s_addc_u32 s23, s9, 0
	v_lshl_or_b32 v134, v3, 3, v5
	v_bfe_u32 v3, v0, 3, 3
	v_lshl_or_b32 v3, v2, 3, v3
	s_ff1_i32_b64 s10, s[6:7]
	s_add_u32 s8, s6, -1
	v_lshlrev_b32_e32 v5, 12, v3
	v_lshrrev_b32_e32 v3, 1, v3
	s_addc_u32 s9, s7, -1
	s_mul_i32 s11, s10, 0x44000
	v_xor_b32_e32 v3, v3, v0
	s_add_u32 s24, s20, s11
	v_lshlrev_b32_e32 v3, 3, v3
	v_lshlrev_b32_e32 v174, 10, v2
	s_addc_u32 s25, s21, 0
	v_ashrrev_i32_e32 v129, 31, v128
	v_and_or_b32 v136, v3, 56, v5
	v_lshl_add_u64 v[2:3], v[128:129], 1, s[24:25]
	v_readfirstlane_b32 s26, v174
	v_lshl_add_u64 v[2:3], v[2:3], 0, s[0:1]
	s_mov_b32 m0, s26
	v_ashrrev_i32_e32 v131, 31, v130
	v_add_u32_e32 v5, 0x1000, v174
	v_add_u32_e32 v132, 0x11000, v128
	global_load_lds_dwordx4 v[2:3], off
	v_lshl_add_u64 v[2:3], v[130:131], 1, s[24:25]
	v_readfirstlane_b32 s26, v5
	v_lshl_add_u64 v[2:3], v[2:3], 0, s[0:1]
	s_mov_b32 m0, s26
	v_ashrrev_i32_e32 v133, 31, v132
	v_add_u32_e32 v5, 0x2000, v174
	global_load_lds_dwordx4 v[2:3], off
	v_lshl_add_u64 v[2:3], v[132:133], 1, s[24:25]
	v_readfirstlane_b32 s26, v5
	v_lshl_add_u64 v[2:3], v[2:3], 0, s[0:1]
	s_mov_b32 m0, s26
	v_ashrrev_i32_e32 v135, 31, v134
	v_add_u32_e32 v5, 0x3000, v174
	s_lshl_b32 s11, s10, 7
	global_load_lds_dwordx4 v[2:3], off
	v_lshl_add_u64 v[2:3], v[134:135], 1, s[24:25]
	v_readfirstlane_b32 s24, v5
	s_mov_b32 m0, s24
	s_add_u32 s24, s22, s11
	v_add_u32_e32 v5, 0x4000, v174
	v_add_u32_e32 v138, 0x20000, v136
	v_lshl_add_u64 v[2:3], v[2:3], 0, s[0:1]
	s_addc_u32 s25, s23, 0
	v_ashrrev_i32_e32 v137, 31, v136
	v_readfirstlane_b32 s11, v5
	v_add_u32_e32 v5, 0x5000, v174
	v_add_u32_e32 v140, 0x40000, v136
	global_load_lds_dwordx4 v[2:3], off
	v_lshl_add_u64 v[2:3], v[136:137], 1, s[24:25]
	s_mov_b32 m0, s11
	v_ashrrev_i32_e32 v139, 31, v138
	v_readfirstlane_b32 s11, v5
	v_add_u32_e32 v5, 0x6000, v174
	v_add_u32_e32 v142, 0x60000, v136
	global_load_lds_dwordx4 v[2:3], off
	v_lshl_add_u64 v[2:3], v[138:139], 1, s[24:25]
	s_mov_b32 m0, s11
	v_ashrrev_i32_e32 v141, 31, v140
	v_readfirstlane_b32 s11, v5
	v_add_u32_e32 v5, 0x7000, v174
	global_load_lds_dwordx4 v[2:3], off
	v_lshl_add_u64 v[2:3], v[140:141], 1, s[24:25]
	s_mov_b32 m0, s11
	v_ashrrev_i32_e32 v143, 31, v142
	v_readfirstlane_b32 s11, v5
	global_load_lds_dwordx4 v[2:3], off
	v_lshl_add_u64 v[2:3], v[142:143], 1, s[24:25]
	s_mov_b32 m0, s11
	v_lshlrev_b32_e32 v5, 1, v0
	global_load_lds_dwordx4 v[2:3], off
	v_lshrrev_b32_e32 v2, 1, v0
	v_bfe_u32 v3, v0, 1, 3
	v_and_b32_e32 v0, 3, v0
	v_and_or_b32 v0, v5, 24, v0
	v_lshlrev_b32_e32 v5, 3, v173
	v_or_b32_e32 v6, v1, v5
	v_bitop3_b32 v5, v1, v4, v5 bitop3:0x36
	v_lshlrev_b32_e32 v179, 8, v0
	v_bitop3_b32 v0, v1, v2, 7 bitop3:0x78
	s_waitcnt vmcnt(0)
	v_lshlrev_b32_e32 v175, 4, v5
	v_bitop3_b32 v5, v6, v4, 4 bitop3:0x36
	v_lshlrev_b32_e32 v180, 4, v0
	v_bitop3_b32 v0, v1, v3, 4 bitop3:0x36
	v_mov_b32_e32 v8, v119
	v_mov_b32_e32 v9, v119
	v_mov_b32_e32 v10, v119
	v_mov_b32_e32 v11, v119
	v_lshlrev_b32_e32 v176, 4, v5
	v_lshlrev_b32_e32 v177, 3, v1
	v_lshlrev_b32_e32 v178, 7, v4
	v_lshlrev_b32_e32 v181, 4, v0
	v_mov_b64_e32 v[14:15], v[10:11]
	v_mov_b64_e32 v[18:19], v[10:11]
	v_mov_b64_e32 v[22:23], v[10:11]
	v_mov_b64_e32 v[26:27], v[10:11]
	v_mov_b64_e32 v[30:31], v[10:11]
	v_mov_b64_e32 v[34:35], v[10:11]
	v_mov_b64_e32 v[38:39], v[10:11]
	v_mov_b64_e32 v[42:43], v[10:11]
	v_mov_b64_e32 v[46:47], v[10:11]
	v_mov_b64_e32 v[50:51], v[10:11]
	v_mov_b64_e32 v[54:55], v[10:11]
	v_mov_b64_e32 v[58:59], v[10:11]
	v_mov_b64_e32 v[62:63], v[10:11]
	v_mov_b64_e32 v[4:5], v[8:9]
	v_mov_b64_e32 v[0:1], v[8:9]
	s_and_b64 s[6:7], s[8:9], s[6:7]
	s_mov_b32 s24, 0
	v_mov_b32_e32 v182, 0xf149f2ca
	v_mov_b32_e32 v144, 0
	v_mov_b64_e32 v[12:13], v[8:9]
	v_mov_b64_e32 v[16:17], v[8:9]
	v_mov_b64_e32 v[20:21], v[8:9]
	v_mov_b64_e32 v[24:25], v[8:9]
	v_mov_b64_e32 v[28:29], v[8:9]
	v_mov_b64_e32 v[32:33], v[8:9]
	v_mov_b64_e32 v[36:37], v[8:9]
	v_mov_b64_e32 v[40:41], v[8:9]
	v_mov_b64_e32 v[44:45], v[8:9]
	v_mov_b64_e32 v[48:49], v[8:9]
	v_mov_b64_e32 v[52:53], v[8:9]
	v_mov_b64_e32 v[56:57], v[8:9]
	v_mov_b64_e32 v[60:61], v[8:9]
	v_mov_b64_e32 v[6:7], v[10:11]
	v_mov_b64_e32 v[2:3], v[10:11]
	v_mov_b32_e32 v145, 0
	v_mov_b32_e32 v183, 0xf149f2ca
	v_lshlrev_b32_e32 v246, 1, v128
	v_lshlrev_b32_e32 v247, 1, v130
	v_lshlrev_b32_e32 v248, 1, v132
	v_lshlrev_b32_e32 v249, 1, v134
	v_lshlrev_b32_e32 v250, 1, v136
	v_lshlrev_b32_e32 v251, 1, v138
	v_lshlrev_b32_e32 v252, 1, v140
	v_lshlrev_b32_e32 v253, 1, v142
	s_waitcnt vmcnt(0) lgkmcnt(0)
	s_barrier
	s_cmp_lg_u64 s[6:7], 0
	s_cbranch_scc1 .LBB0_822
	s_branch .LBB0_821
	.p2alignl 6, 3212836864

; template <class Epi>
; __device__ __forceinline__ void gemm_tile(const bf16_t* __restrict__ A, const bf16_t* __restrict__ Bt, int K, int row0, int col0, const Epi& epi, char* smem,
;                                           bool prefetched, bool nvalid, int nrow0, int ncol0) {
;     ...
;     for (int kt = 0; kt < nk; ++kt) {
;         const int cur = kt & 1;
;         if (kt + 1 < nk) GLDS_STAGE(cur ^ 1, pA, pB, kt + 1);
;         const char* cb = smem + cur * 2 * TILE_B;
; #pragma unroll
;         for (int ks = 0; ks < 2; ++ks) {
;             bf16x8 a[4], b[4];
; #pragma unroll
;             for (int m = 0; m < 4; ++m) a[m] = *(const bf16x8*)(cb + offA[m][ks]);
; #pragma unroll
;             for (int n = 0; n < 4; ++n) b[n] = *(const bf16x8*)(cb + offB[n][ks]);
.LBB0_998:
	v_readfirstlane_b32 s98, v106
	v_readfirstlane_b32 s99, v107
	v_readfirstlane_b32 s10, v108
	v_readfirstlane_b32 s100, v120
	v_readfirstlane_b32 s101, v121
	v_readfirstlane_b32 s17, v149
	s_nop 3
	s_sub_u32 s18, s10, s98
	s_and_b32 s98, s98, 0xffffff80
	s_and_b32 s100, s100, 0xffffff80
	s_nop 1
	v_subrev_u32_e32 v254, s98, v106
	v_subrev_u32_e32 v255, s100, v120
	s_add_i32 s13, s17, 0x8000
	s_mov_b32 m0, s13
	s_nop 0
	global_load_lds_dwordx4 v254, s[98:99]
	s_add_i32 m0, s13, 0x1000
	s_add_u32 s10, s98, s18
	s_addc_u32 s11, s99, 0
	global_load_lds_dwordx4 v254, s[10:11]
	s_add_i32 m0, s13, 0x2000
	s_add_u32 s10, s10, s18
	s_addc_u32 s11, s11, 0
	global_load_lds_dwordx4 v254, s[10:11]
	s_add_i32 m0, s13, 0x3000
	s_add_u32 s10, s10, s18
	s_addc_u32 s11, s11, 0
	global_load_lds_dwordx4 v254, s[10:11]
	s_add_u32 s98, s98, 0x80
	s_addc_u32 s99, s99, 0
	ds_read_b128 v[184:187], v130
	ds_read_b128 v[106:109], v133 offset:16384
	ds_read_b128 v[118:121], v133 offset:16896
	ds_read_b128 v[122:125], v133 offset:20480
	ds_read_b128 v[158:161], v133 offset:20992
	ds_read_b128 v[188:191], v130 offset:2048
	ds_read_b128 v[246:249], v130 offset:4096
	ds_read_b128 v[250:253], v130 offset:6144
	s_setprio 1
	.p2alignl 6, 3212836864

; template <class Epi>
; __device__ __forceinline__ void gemm_tile(const bf16_t* __restrict__ A, const bf16_t* __restrict__ Bt, int K, int row0, int col0, const Epi& epi, char* smem,
;                                           bool prefetched, bool nvalid, int nrow0, int ncol0) {
;     ...
;     for (int kt = 0; kt < nk; ++kt) {
;         const int cur = kt & 1;
;         if (kt + 1 < nk) GLDS_STAGE(cur ^ 1, pA, pB, kt + 1);
;         const char* cb = smem + cur * 2 * TILE_B;
; #pragma unroll
;         for (int ks = 0; ks < 2; ++ks) {
;             bf16x8 a[4], b[4];
; #pragma unroll
;             for (int m = 0; m < 4; ++m) a[m] = *(const bf16x8*)(cb + offA[m][ks]);
; #pragma unroll
;             for (int n = 0; n < 4; ++n) b[n] = *(const bf16x8*)(cb + offB[n][ks]);
.LBB0_1054:
	v_readfirstlane_b32 s98, v92
	v_readfirstlane_b32 s99, v93
	v_readfirstlane_b32 s6, v94
	v_readfirstlane_b32 s100, v100
	v_readfirstlane_b32 s101, v101
	v_readfirstlane_b32 s10, v149
	s_nop 3
	s_sub_u32 s11, s6, s98
	s_and_b32 s98, s98, 0xffffff80
	s_and_b32 s100, s100, 0xffffff80
	s_nop 1
	v_subrev_u32_e32 v254, s98, v92
	v_subrev_u32_e32 v255, s100, v100
	s_add_i32 s9, s10, 0x8000
	s_mov_b32 m0, s9
	s_nop 0
	global_load_lds_dwordx4 v254, s[98:99]
	s_add_i32 m0, s9, 0x1000
	s_add_u32 s6, s98, s11
	s_addc_u32 s7, s99, 0
	global_load_lds_dwordx4 v254, s[6:7]
	s_add_i32 m0, s9, 0x2000
	s_add_u32 s6, s6, s11
	s_addc_u32 s7, s7, 0
	global_load_lds_dwordx4 v254, s[6:7]
	s_add_i32 m0, s9, 0x3000
	s_add_u32 s6, s6, s11
	s_addc_u32 s7, s7, 0
	global_load_lds_dwordx4 v254, s[6:7]
	s_add_u32 s98, s98, 0x80
	s_addc_u32 s99, s99, 0
	ds_read_b128 v[150:153], v108
	ds_read_b128 v[92:95], v110 offset:16384
	ds_read_b128 v[96:99], v110 offset:16896
	ds_read_b128 v[100:103], v110 offset:20480
	ds_read_b128 v[104:107], v110 offset:20992
	ds_read_b128 v[154:157], v108 offset:2048
	ds_read_b128 v[246:249], v108 offset:4096
	ds_read_b128 v[250:253], v108 offset:6144
	s_setprio 1
	.p2alignl 6, 3212836864
